# ffn_act row loop unrolled by 4 over 4 register buffers with the row four ahead requested after each store
# baseline (speedup 1.0000x reference)
; DI void unpack8(u32x4 w, float* v) { v[0] = lo16(w.x); v[1] = hi16(w.x); v[2] = lo16(w.y); v[3] = hi16(w.y); v[4] = lo16(w.z); v[5] = hi16(w.z); v[6] = lo16(w.w); v[7] = hi16(w.w); }
; DI u32x4 pack8(const float* v) { u32x4 w; w.x = pk2(v[0], v[1]); w.y = pk2(v[2], v[3]); w.z = pk2(v[4], v[5]); w.w = pk2(v[6], v[7]); return w; }
; DI float silu(float x) { return x * __builtin_amdgcn_rcpf(1.f + fexp(-x)); }
; DI void ffn_act(CP c, int l, int bid, int nb) {
;     ...
;     const int rows_per = (MT + ngroups - 1) / ngroups; const int r0 = rg * rows_per; const int r1 = (r0 + rows_per < MT) ? r0 + rows_per : MT;
;     float w0[8], w1[8], w2[8], bb[8], a0[8], a1[8];
; #pragma unroll
;     for (int j = 0; j < 8; ++j) { w0[j] = cw[cc + j]; w1[j] = cw[DFF + cc + j]; w2[j] = cw[2 * DFF + cc + j]; bb[j] = cb[cc + j]; a0[j] = 0.f; a1[j] = 0.f; }
;     for (int r = r0; r < r1; ++r) {
;         const bool samp = r >= MP; const int b = (r - MP) >> 4, t = samp ? (r - MP) & 15 : r;
;         float a2[8], vv[8], o[8];
;         unpack8(*(const u32x4*)(UP + (size_t)r * 5632 + cc), a2); unpack8(*(const u32x4*)(UP + (size_t)r * 5632 + DFF + cc), vv);
;         if (r == r0 || (samp && t == 0)) {
;             if (t >= 1) unpack8(*(const u32x4*)(UP + (size_t)(r - 1) * 5632 + cc), a1);
;             else {
; #pragma unroll
;                 for (int j = 0; j < 8; ++j) a1[j] = samp ? c->in[I_SFFN][((size_t)(l * 32 + b) * 2 + 1) * DFF + cc + j] : 0.f; }
;             if (t >= 2) unpack8(*(const u32x4*)(UP + (size_t)(r - 2) * 5632 + cc), a0);
;             else {
; #pragma unroll
;                 for (int j = 0; j < 8; ++j) a0[j] = samp ? c->in[I_SFFN][((size_t)(l * 32 + b) * 2 + t) * DFF + cc + j] : 0.f; }
;         }
; #pragma unroll
;         for (int j = 0; j < 8; ++j) { const float y = w0[j] * a0[j] + w1[j] * a1[j] + w2[j] * a2[j] + bb[j]; o[j] = silu(y) * vv[j]; a0[j] = a1[j]; a1[j] = a2[j]; }
;         *(u32x4*)(ACT + (size_t)r * DFF + cc) = pack8(o);
.LBB0_478:
	s_or_b64 exec, exec, s[12:13]
	v_add_u32_e32 v75, 1, v70
	v_cmp_lt_i32_e32 vcc, v75, v74
	s_and_b64 exec, exec, vcc
	s_cbranch_execz .LBB0_489
	s_movk_i32 s12, 0x1600
	v_mad_i64_i32 v[18:19], s[12:13], v75, s12, v[62:63]
	v_lshl_add_u64 v[70:71], s[8:9], 0, v[18:19]
	s_movk_i32 s8, 0x2c00
	v_mad_i64_i32 v[18:19], s[8:9], v75, s8, v[62:63]
	v_lshl_add_u64 v[18:19], s[20:21], 0, v[18:19]
	s_mov_b64 s[8:9], 0x2e55600
	v_lshl_add_u64 v[72:73], v[18:19], 0, s[8:9]
	s_mov_b64 s[8:9], 0
	v_add_co_u32_e32 v114, vcc, 0xffffea00, v72
	s_nop 1
	v_addc_co_u32_e32 v115, vcc, -1, v73, vcc
	global_load_dwordx4 v[82:85], v[114:115], off
	global_load_dwordx4 v[86:89], v[72:73], off
	v_add_co_u32_e32 v114, vcc, 0x1600, v72
	s_nop 1
	v_addc_co_u32_e32 v115, vcc, 0, v73, vcc
	global_load_dwordx4 v[90:93], v[114:115], off
	v_add_co_u32_e32 v114, vcc, 0x2c00, v72
	s_nop 1
	v_addc_co_u32_e32 v115, vcc, 0, v73, vcc
	global_load_dwordx4 v[94:97], v[114:115], off
	v_add_co_u32_e32 v114, vcc, 0x4200, v72
	s_nop 1
	v_addc_co_u32_e32 v115, vcc, 0, v73, vcc
	global_load_dwordx4 v[98:101], v[114:115], off
	v_add_co_u32_e32 v114, vcc, 0x5800, v72
	s_nop 1
	v_addc_co_u32_e32 v115, vcc, 0, v73, vcc
	global_load_dwordx4 v[102:105], v[114:115], off
	v_add_co_u32_e32 v114, vcc, 0x6e00, v72
	s_nop 1
	v_addc_co_u32_e32 v115, vcc, 0, v73, vcc
	global_load_dwordx4 v[106:109], v[114:115], off
	v_add_co_u32_e32 v114, vcc, 0x8400, v72
	s_nop 1
	v_addc_co_u32_e32 v115, vcc, 0, v73, vcc
	global_load_dwordx4 v[110:113], v[114:115], off
	s_branch .Lffn0_481
.Lffn0_481:
	s_waitcnt vmcnt(6)
	v_add_u32_e32 v0, 0xffffc000, v75
	v_ashrrev_i32_e32 v76, 4, v0
	v_and_b32_e32 v0, 15, v75
	v_cmp_lt_i32_e64 s[38:39], s3, v75
	v_mov_b64_e32 v[24:25], v[8:9]
	v_mov_b64_e32 v[22:23], v[6:7]
	v_cndmask_b32_e64 v77, v75, v0, s[38:39]
	v_cmp_eq_u32_e32 vcc, 0, v77
	v_mov_b64_e32 v[20:21], v[4:5]
	v_mov_b64_e32 v[18:19], v[2:3]
	v_mov_b64_e32 v[2:3], v[10:11]
	s_and_b64 s[16:17], s[38:39], vcc
	v_mov_b64_e32 v[4:5], v[12:13]
	v_mov_b64_e32 v[6:7], v[14:15]
	v_mov_b64_e32 v[8:9], v[16:17]
	s_and_saveexec_b64 s[12:13], s[16:17]
	s_cbranch_execz .Lffn0_483
	s_load_dwordx2 s[16:17], s[46:47], 0x38
	v_readlane_b32 s14, v255, 6
	s_waitcnt lgkmcnt(0)
	v_mov_b64_e32 v[12:13], s[16:17]
	v_add_u32_e32 v10, s14, v76
	s_movk_i32 s14, 0x5800
	v_ashrrev_i32_e32 v11, 31, v10
	v_mad_i64_i32 v[2:3], s[16:17], v10, s14, v[12:13]
	v_lshl_add_u64 v[2:3], v[2:3], 0, v[68:69]
	s_mov_b64 s[16:17], 0x2c00
	v_lshl_add_u64 v[10:11], v[10:11], 1, v[0:1]
	s_movk_i32 s14, 0x2c00
	v_lshl_add_u64 v[6:7], v[2:3], 0, s[16:17]
	v_mad_u64_u32 v[12:13], s[16:17], v10, s14, v[12:13]
	v_add_co_u32_e32 v2, vcc, 0x2000, v2
	v_mad_i32_i24 v13, v11, s14, v13
	s_nop 0
	v_addc_co_u32_e32 v3, vcc, 0, v3, vcc
	v_lshl_add_u64 v[10:11], v[12:13], 0, v[68:69]
	global_load_dwordx4 v[2:5], v[2:3], off offset:3072
	s_nop 0
	global_load_dwordx4 v[6:9], v[6:7], off offset:16
	s_nop 0
	global_load_dwordx4 v[22:25], v[10:11], off offset:16
	global_load_dwordx4 v[18:21], v[10:11], off
	s_waitcnt vmcnt(0)
.Lffn0_483:
	s_or_b64 exec, exec, s[12:13]
	v_pk_mul_f32 v[78:79], v[34:35], v[2:3]
	v_lshlrev_b32_e32 v10, 16, v82
	v_and_b32_e32 v11, 0xffff0000, v82
	v_pk_fma_f32 v[18:19], v[30:31], v[18:19], v[78:79]
	v_lshlrev_b32_e32 v12, 16, v83
	v_pk_fma_f32 v[18:19], v[38:39], v[10:11], v[18:19]
	v_and_b32_e32 v13, 0xffff0000, v83
	v_pk_add_f32 v[18:19], v[54:55], v[18:19]
	v_lshlrev_b32_e32 v82, 16, v86
	v_mul_f32_e32 v78, 0xbfb8aa3b, v18
	v_mul_f32_e32 v79, 0xbfb8aa3b, v19
	v_exp_f32_e32 v78, v78
	v_exp_f32_e32 v79, v79
	v_and_b32_e32 v83, 0xffff0000, v86
	v_lshlrev_b32_e32 v86, 16, v87
	v_add_f32_e32 v78, 1.0, v78
	v_add_f32_e32 v79, 1.0, v79
	v_rcp_f32_e32 v78, v78
	v_rcp_f32_e32 v79, v79
	v_and_b32_e32 v87, 0xffff0000, v87
	v_lshlrev_b32_e32 v14, 16, v84
	v_and_b32_e32 v15, 0xffff0000, v84
	v_pk_mul_f32 v[18:19], v[18:19], v[78:79]
	v_lshlrev_b32_e32 v16, 16, v85
	v_pk_mul_f32 v[18:19], v[18:19], v[82:83]
	v_pk_mul_f32 v[82:83], v[36:37], v[4:5]
	v_and_b32_e32 v17, 0xffff0000, v85
	v_pk_fma_f32 v[20:21], v[32:33], v[20:21], v[82:83]
	v_lshlrev_b32_e32 v84, 16, v88
	v_pk_fma_f32 v[20:21], v[40:41], v[12:13], v[20:21]
	v_and_b32_e32 v85, 0xffff0000, v88
	v_pk_add_f32 v[20:21], v[56:57], v[20:21]
	v_lshlrev_b32_e32 v88, 16, v89
	v_mul_f32_e32 v82, 0xbfb8aa3b, v20
	v_mul_f32_e32 v83, 0xbfb8aa3b, v21
	v_exp_f32_e32 v82, v82
	v_exp_f32_e32 v83, v83
	v_and_b32_e32 v89, 0xffff0000, v89
	s_movk_i32 s12, 0x3ffd
	v_add_f32_e32 v82, 1.0, v82
	v_add_f32_e32 v83, 1.0, v83
	v_rcp_f32_e32 v82, v82
	v_rcp_f32_e32 v83, v83
	v_cvt_pk_bf16_f32 v18, v18, v19
	v_cmp_lt_i32_e32 vcc, s12, v75
	s_xor_b64 s[16:17], s[38:39], vcc
	v_pk_mul_f32 v[20:21], v[20:21], v[82:83]
	s_nop 0
	v_pk_mul_f32 v[20:21], v[20:21], v[86:87]
	v_pk_mul_f32 v[86:87], v[42:43], v[6:7]
	v_cvt_pk_bf16_f32 v19, v20, v21
	v_pk_fma_f32 v[22:23], v[26:27], v[22:23], v[86:87]
	s_nop 0
	v_pk_fma_f32 v[22:23], v[46:47], v[14:15], v[22:23]
	s_nop 0
	v_pk_add_f32 v[22:23], v[50:51], v[22:23]
	s_nop 0
	v_mul_f32_e32 v86, 0xbfb8aa3b, v22
	v_mul_f32_e32 v87, 0xbfb8aa3b, v23
	v_exp_f32_e32 v86, v86
	v_exp_f32_e32 v87, v87
	v_add_f32_e32 v86, 1.0, v86
	v_add_f32_e32 v87, 1.0, v87
	v_rcp_f32_e32 v86, v86
	v_rcp_f32_e32 v87, v87
	s_nop 0
	v_pk_mul_f32 v[22:23], v[22:23], v[86:87]
	v_pk_mul_f32 v[86:87], v[44:45], v[8:9]
	v_pk_mul_f32 v[22:23], v[22:23], v[84:85]
	v_pk_fma_f32 v[24:25], v[28:29], v[24:25], v[86:87]
	v_cvt_pk_bf16_f32 v20, v22, v23
	v_pk_fma_f32 v[24:25], v[48:49], v[16:17], v[24:25]
	s_nop 0
	v_pk_add_f32 v[24:25], v[52:53], v[24:25]
	s_nop 0
	v_mul_f32_e32 v86, 0xbfb8aa3b, v24
	v_mul_f32_e32 v87, 0xbfb8aa3b, v25
	v_exp_f32_e32 v86, v86
	v_exp_f32_e32 v87, v87
	v_add_f32_e32 v86, 1.0, v86
	v_add_f32_e32 v87, 1.0, v87
	v_rcp_f32_e32 v86, v86
	v_rcp_f32_e32 v87, v87
	s_nop 0
	v_pk_mul_f32 v[24:25], v[24:25], v[86:87]
	s_nop 0
	v_pk_mul_f32 v[24:25], v[24:25], v[88:89]
	s_nop 0
	v_cvt_pk_bf16_f32 v21, v24, v25
	global_store_dwordx4 v[70:71], v[18:21], off
	v_add_co_u32_e32 v114, vcc, 0x9a00, v72
	s_nop 1
	v_addc_co_u32_e32 v115, vcc, 0, v73, vcc
	global_load_dwordx4 v[82:85], v[114:115], off
	v_add_co_u32_e32 v114, vcc, 0xb000, v72
	s_nop 1
	v_addc_co_u32_e32 v115, vcc, 0, v73, vcc
	global_load_dwordx4 v[86:89], v[114:115], off
	s_nop 1
	v_mov_b64_e32 v[18:19], 0
	s_and_saveexec_b64 s[12:13], s[16:17]
	s_cbranch_execz .Lffn0_485
	s_load_dwordx2 s[16:17], s[46:47], 0x128
	v_add_u32_e32 v18, 0xffffc002, v75
	v_mov_b32_e32 v19, v1
	v_lshl_add_u64 v[18:19], s[6:7], 0, v[18:19]
	s_movk_i32 s14, 0x2c00
	s_waitcnt lgkmcnt(0)
	v_mov_b64_e32 v[20:21], s[16:17]
	v_mad_u64_u32 v[20:21], s[16:17], v18, s14, v[20:21]
	v_mad_i32_i24 v21, v19, s14, v21
	v_lshl_add_u64 v[18:19], v[66:67], 2, v[20:21]
	s_mov_b64 s[16:17], 0x6aa7000
	v_lshl_add_u64 v[18:19], v[18:19], 0, s[16:17]

; DI void ffn_act(CP c, int l, int bid, int nb) {
;     ...
;     for (int r = r0; r < r1; ++r) {
;     ...
;         float* so = nullptr;
;         if (!samp && r >= MP - 2) so = c->out + O_PFFN + ((size_t)l * 2 + (r - (MP - 2))) * DFF + cc;
;         if (samp && t >= 14) so = c->out + O_SFFN + ((size_t)(l * 32 + b) * 2 + (t - 14)) * DFF + cc;
;         if (so) {
; #pragma unroll
;             for (int j = 0; j < 8; ++j) so[j] = a2[j]; }
;     }
.Lffn0_487:
	s_or_b64 exec, exec, s[12:13]
	v_cmp_ne_u64_e32 vcc, 0, v[18:19]
	s_and_saveexec_b64 s[12:13], vcc
	s_cbranch_execz .Lffn0_480
	global_store_dwordx4 v[18:19], v[10:13], off
	global_store_dwordx4 v[18:19], v[14:17], off offset:16
	s_branch .Lffn0_480
.Lffn0_480:
	s_or_b64 exec, exec, s[12:13]
	v_add_u32_e32 v75, 1, v75
	s_mov_b64 s[12:13], 0x1600
	v_lshl_add_u64 v[70:71], v[70:71], 0, s[12:13]
	v_cmp_ge_i32_e32 vcc, v75, v74
	s_mov_b64 s[12:13], 0x2c00
	s_or_b64 s[8:9], vcc, s[8:9]
	v_lshl_add_u64 v[72:73], v[72:73], 0, s[12:13]
	s_andn2_b64 exec, exec, s[8:9]
	s_cbranch_execz .LBB0_489

; DI void unpack8(u32x4 w, float* v) { v[0] = lo16(w.x); v[1] = hi16(w.x); v[2] = lo16(w.y); v[3] = hi16(w.y); v[4] = lo16(w.z); v[5] = hi16(w.z); v[6] = lo16(w.w); v[7] = hi16(w.w); }
; DI u32x4 pack8(const float* v) { u32x4 w; w.x = pk2(v[0], v[1]); w.y = pk2(v[2], v[3]); w.z = pk2(v[4], v[5]); w.w = pk2(v[6], v[7]); return w; }
; DI float silu(float x) { return x * __builtin_amdgcn_rcpf(1.f + fexp(-x)); }
; DI void ffn_act(CP c, int l, int bid, int nb) {
;     ...
;         const bool samp = r >= MP; const int b = (r - MP) >> 4, t = samp ? (r - MP) & 15 : r;
;         float a2[8], vv[8], o[8];
;         unpack8(*(const u32x4*)(UP + (size_t)r * 5632 + cc), a2); unpack8(*(const u32x4*)(UP + (size_t)r * 5632 + DFF + cc), vv);
;         if (r == r0 || (samp && t == 0)) {
;             if (t >= 1) unpack8(*(const u32x4*)(UP + (size_t)(r - 1) * 5632 + cc), a1);
;             else {
; #pragma unroll
;                 for (int j = 0; j < 8; ++j) a1[j] = samp ? c->in[I_SFFN][((size_t)(l * 32 + b) * 2 + 1) * DFF + cc + j] : 0.f; }
;             if (t >= 2) unpack8(*(const u32x4*)(UP + (size_t)(r - 2) * 5632 + cc), a0);
;             else {
; #pragma unroll
;                 for (int j = 0; j < 8; ++j) a0[j] = samp ? c->in[I_SFFN][((size_t)(l * 32 + b) * 2 + t) * DFF + cc + j] : 0.f; }
;         }
; #pragma unroll
;         for (int j = 0; j < 8; ++j) { const float y = w0[j] * a0[j] + w1[j] * a1[j] + w2[j] * a2[j] + bb[j]; o[j] = silu(y) * vv[j]; a0[j] = a1[j]; a1[j] = a2[j]; }
;         *(u32x4*)(ACT + (size_t)r * DFF + cc) = pack8(o);
.Lffn1_483:
	s_or_b64 exec, exec, s[12:13]
	v_pk_mul_f32 v[78:79], v[34:35], v[2:3]
	v_lshlrev_b32_e32 v10, 16, v90
	v_and_b32_e32 v11, 0xffff0000, v90
	v_pk_fma_f32 v[18:19], v[30:31], v[18:19], v[78:79]
	v_lshlrev_b32_e32 v12, 16, v91
	v_pk_fma_f32 v[18:19], v[38:39], v[10:11], v[18:19]
	v_and_b32_e32 v13, 0xffff0000, v91
	v_pk_add_f32 v[18:19], v[54:55], v[18:19]
	v_lshlrev_b32_e32 v90, 16, v94
	v_mul_f32_e32 v78, 0xbfb8aa3b, v18
	v_mul_f32_e32 v79, 0xbfb8aa3b, v19
	v_exp_f32_e32 v78, v78
	v_exp_f32_e32 v79, v79
	v_and_b32_e32 v91, 0xffff0000, v94
	v_lshlrev_b32_e32 v94, 16, v95
	v_add_f32_e32 v78, 1.0, v78
	v_add_f32_e32 v79, 1.0, v79
	v_rcp_f32_e32 v78, v78
	v_rcp_f32_e32 v79, v79
	v_and_b32_e32 v95, 0xffff0000, v95
	v_lshlrev_b32_e32 v14, 16, v92
	v_and_b32_e32 v15, 0xffff0000, v92
	v_pk_mul_f32 v[18:19], v[18:19], v[78:79]
	v_lshlrev_b32_e32 v16, 16, v93
	v_pk_mul_f32 v[18:19], v[18:19], v[90:91]
	v_pk_mul_f32 v[90:91], v[36:37], v[4:5]
	v_and_b32_e32 v17, 0xffff0000, v93
	v_pk_fma_f32 v[20:21], v[32:33], v[20:21], v[90:91]
	v_lshlrev_b32_e32 v92, 16, v96
	v_pk_fma_f32 v[20:21], v[40:41], v[12:13], v[20:21]
	v_and_b32_e32 v93, 0xffff0000, v96
	v_pk_add_f32 v[20:21], v[56:57], v[20:21]
	v_lshlrev_b32_e32 v96, 16, v97
	v_mul_f32_e32 v90, 0xbfb8aa3b, v20
	v_mul_f32_e32 v91, 0xbfb8aa3b, v21
	v_exp_f32_e32 v90, v90
	v_exp_f32_e32 v91, v91
	v_and_b32_e32 v97, 0xffff0000, v97
	s_movk_i32 s12, 0x3ffd
	v_add_f32_e32 v90, 1.0, v90
	v_add_f32_e32 v91, 1.0, v91
	v_rcp_f32_e32 v90, v90
	v_rcp_f32_e32 v91, v91
	v_cvt_pk_bf16_f32 v18, v18, v19
	v_cmp_lt_i32_e32 vcc, s12, v75
	s_xor_b64 s[16:17], s[38:39], vcc
	v_pk_mul_f32 v[20:21], v[20:21], v[90:91]
	s_nop 0
	v_pk_mul_f32 v[20:21], v[20:21], v[94:95]
	v_pk_mul_f32 v[94:95], v[42:43], v[6:7]
	v_cvt_pk_bf16_f32 v19, v20, v21
	v_pk_fma_f32 v[22:23], v[26:27], v[22:23], v[94:95]
	s_nop 0
	v_pk_fma_f32 v[22:23], v[46:47], v[14:15], v[22:23]
	s_nop 0
	v_pk_add_f32 v[22:23], v[50:51], v[22:23]
	s_nop 0
	v_mul_f32_e32 v94, 0xbfb8aa3b, v22
	v_mul_f32_e32 v95, 0xbfb8aa3b, v23
	v_exp_f32_e32 v94, v94
	v_exp_f32_e32 v95, v95
	v_add_f32_e32 v94, 1.0, v94
	v_add_f32_e32 v95, 1.0, v95
	v_rcp_f32_e32 v94, v94
	v_rcp_f32_e32 v95, v95
	s_nop 0
	v_pk_mul_f32 v[22:23], v[22:23], v[94:95]
	v_pk_mul_f32 v[94:95], v[44:45], v[8:9]
	v_pk_mul_f32 v[22:23], v[22:23], v[92:93]
	v_pk_fma_f32 v[24:25], v[28:29], v[24:25], v[94:95]
	v_cvt_pk_bf16_f32 v20, v22, v23
	v_pk_fma_f32 v[24:25], v[48:49], v[16:17], v[24:25]
	s_nop 0
	v_pk_add_f32 v[24:25], v[52:53], v[24:25]
	s_nop 0
	v_mul_f32_e32 v94, 0xbfb8aa3b, v24
	v_mul_f32_e32 v95, 0xbfb8aa3b, v25
	v_exp_f32_e32 v94, v94
	v_exp_f32_e32 v95, v95
	v_add_f32_e32 v94, 1.0, v94
	v_add_f32_e32 v95, 1.0, v95
	v_rcp_f32_e32 v94, v94
	v_rcp_f32_e32 v95, v95
	s_nop 0
	v_pk_mul_f32 v[24:25], v[24:25], v[94:95]
	s_nop 0
	v_pk_mul_f32 v[24:25], v[24:25], v[96:97]
	s_nop 0
	v_cvt_pk_bf16_f32 v21, v24, v25
	global_store_dwordx4 v[70:71], v[18:21], off
	v_add_co_u32_e32 v114, vcc, 0x9a00, v72
	s_nop 1
	v_addc_co_u32_e32 v115, vcc, 0, v73, vcc
	global_load_dwordx4 v[90:93], v[114:115], off
	v_add_co_u32_e32 v114, vcc, 0xb000, v72
	s_nop 1
	v_addc_co_u32_e32 v115, vcc, 0, v73, vcc
	global_load_dwordx4 v[94:97], v[114:115], off
	s_nop 1
	v_mov_b64_e32 v[18:19], 0
	s_and_saveexec_b64 s[12:13], s[16:17]
	s_cbranch_execz .Lffn1_485
	s_load_dwordx2 s[16:17], s[46:47], 0x128
	v_add_u32_e32 v18, 0xffffc002, v75
	v_mov_b32_e32 v19, v1
	v_lshl_add_u64 v[18:19], s[6:7], 0, v[18:19]
	s_movk_i32 s14, 0x2c00
	s_waitcnt lgkmcnt(0)
	v_mov_b64_e32 v[20:21], s[16:17]
	v_mad_u64_u32 v[20:21], s[16:17], v18, s14, v[20:21]
	v_mad_i32_i24 v21, v19, s14, v21
	v_lshl_add_u64 v[18:19], v[66:67], 2, v[20:21]
	s_mov_b64 s[16:17], 0x6aa7000
	v_lshl_add_u64 v[18:19], v[18:19], 0, s[16:17]

; DI void ffn_act(CP c, int l, int bid, int nb) {
;     ...
;     for (int r = r0; r < r1; ++r) {
;     ...
;         if (so) {
; #pragma unroll
;             for (int j = 0; j < 8; ++j) so[j] = a2[j]; }
;     }
.Lffn1_487:
	s_or_b64 exec, exec, s[12:13]
	v_cmp_ne_u64_e32 vcc, 0, v[18:19]
	s_and_saveexec_b64 s[12:13], vcc
	s_cbranch_execz .Lffn1_480
	global_store_dwordx4 v[18:19], v[10:13], off
	global_store_dwordx4 v[18:19], v[14:17], off offset:16
	s_branch .Lffn1_480
.Lffn1_480:
	s_or_b64 exec, exec, s[12:13]
	v_add_u32_e32 v75, 1, v75
	s_mov_b64 s[12:13], 0x1600
	v_lshl_add_u64 v[70:71], v[70:71], 0, s[12:13]
	v_cmp_ge_i32_e32 vcc, v75, v74
	s_mov_b64 s[12:13], 0x2c00
	s_or_b64 s[8:9], vcc, s[8:9]
	v_lshl_add_u64 v[72:73], v[72:73], 0, s[12:13]
	s_andn2_b64 exec, exec, s[8:9]
	s_cbranch_execz .LBB0_489

; DI void unpack8(u32x4 w, float* v) { v[0] = lo16(w.x); v[1] = hi16(w.x); v[2] = lo16(w.y); v[3] = hi16(w.y); v[4] = lo16(w.z); v[5] = hi16(w.z); v[6] = lo16(w.w); v[7] = hi16(w.w); }
; DI u32x4 pack8(const float* v) { u32x4 w; w.x = pk2(v[0], v[1]); w.y = pk2(v[2], v[3]); w.z = pk2(v[4], v[5]); w.w = pk2(v[6], v[7]); return w; }
; DI float silu(float x) { return x * __builtin_amdgcn_rcpf(1.f + fexp(-x)); }
; DI void ffn_act(CP c, int l, int bid, int nb) {
;     ...
;         const bool samp = r >= MP; const int b = (r - MP) >> 4, t = samp ? (r - MP) & 15 : r;
;         float a2[8], vv[8], o[8];
;         unpack8(*(const u32x4*)(UP + (size_t)r * 5632 + cc), a2); unpack8(*(const u32x4*)(UP + (size_t)r * 5632 + DFF + cc), vv);
;         if (r == r0 || (samp && t == 0)) {
;             if (t >= 1) unpack8(*(const u32x4*)(UP + (size_t)(r - 1) * 5632 + cc), a1);
;             else {
; #pragma unroll
;                 for (int j = 0; j < 8; ++j) a1[j] = samp ? c->in[I_SFFN][((size_t)(l * 32 + b) * 2 + 1) * DFF + cc + j] : 0.f; }
;             if (t >= 2) unpack8(*(const u32x4*)(UP + (size_t)(r - 2) * 5632 + cc), a0);
;             else {
; #pragma unroll
;                 for (int j = 0; j < 8; ++j) a0[j] = samp ? c->in[I_SFFN][((size_t)(l * 32 + b) * 2 + t) * DFF + cc + j] : 0.f; }
;         }
; #pragma unroll
;         for (int j = 0; j < 8; ++j) { const float y = w0[j] * a0[j] + w1[j] * a1[j] + w2[j] * a2[j] + bb[j]; o[j] = silu(y) * vv[j]; a0[j] = a1[j]; a1[j] = a2[j]; }
;         *(u32x4*)(ACT + (size_t)r * DFF + cc) = pack8(o);
.Lffn2_483:
	s_or_b64 exec, exec, s[12:13]
	v_pk_mul_f32 v[78:79], v[34:35], v[2:3]
	v_lshlrev_b32_e32 v10, 16, v98
	v_and_b32_e32 v11, 0xffff0000, v98
	v_pk_fma_f32 v[18:19], v[30:31], v[18:19], v[78:79]
	v_lshlrev_b32_e32 v12, 16, v99
	v_pk_fma_f32 v[18:19], v[38:39], v[10:11], v[18:19]
	v_and_b32_e32 v13, 0xffff0000, v99
	v_pk_add_f32 v[18:19], v[54:55], v[18:19]
	v_lshlrev_b32_e32 v98, 16, v102
	v_mul_f32_e32 v78, 0xbfb8aa3b, v18
	v_mul_f32_e32 v79, 0xbfb8aa3b, v19
	v_exp_f32_e32 v78, v78
	v_exp_f32_e32 v79, v79
	v_and_b32_e32 v99, 0xffff0000, v102
	v_lshlrev_b32_e32 v102, 16, v103
	v_add_f32_e32 v78, 1.0, v78
	v_add_f32_e32 v79, 1.0, v79
	v_rcp_f32_e32 v78, v78
	v_rcp_f32_e32 v79, v79
	v_and_b32_e32 v103, 0xffff0000, v103
	v_lshlrev_b32_e32 v14, 16, v100
	v_and_b32_e32 v15, 0xffff0000, v100
	v_pk_mul_f32 v[18:19], v[18:19], v[78:79]
	v_lshlrev_b32_e32 v16, 16, v101
	v_pk_mul_f32 v[18:19], v[18:19], v[98:99]
	v_pk_mul_f32 v[98:99], v[36:37], v[4:5]
	v_and_b32_e32 v17, 0xffff0000, v101
	v_pk_fma_f32 v[20:21], v[32:33], v[20:21], v[98:99]
	v_lshlrev_b32_e32 v100, 16, v104
	v_pk_fma_f32 v[20:21], v[40:41], v[12:13], v[20:21]
	v_and_b32_e32 v101, 0xffff0000, v104
	v_pk_add_f32 v[20:21], v[56:57], v[20:21]
	v_lshlrev_b32_e32 v104, 16, v105
	v_mul_f32_e32 v98, 0xbfb8aa3b, v20
	v_mul_f32_e32 v99, 0xbfb8aa3b, v21
	v_exp_f32_e32 v98, v98
	v_exp_f32_e32 v99, v99
	v_and_b32_e32 v105, 0xffff0000, v105
	s_movk_i32 s12, 0x3ffd
	v_add_f32_e32 v98, 1.0, v98
	v_add_f32_e32 v99, 1.0, v99
	v_rcp_f32_e32 v98, v98
	v_rcp_f32_e32 v99, v99
	v_cvt_pk_bf16_f32 v18, v18, v19
	v_cmp_lt_i32_e32 vcc, s12, v75
	s_xor_b64 s[16:17], s[38:39], vcc
	v_pk_mul_f32 v[20:21], v[20:21], v[98:99]
	s_nop 0
	v_pk_mul_f32 v[20:21], v[20:21], v[102:103]
	v_pk_mul_f32 v[102:103], v[42:43], v[6:7]
	v_cvt_pk_bf16_f32 v19, v20, v21
	v_pk_fma_f32 v[22:23], v[26:27], v[22:23], v[102:103]
	s_nop 0
	v_pk_fma_f32 v[22:23], v[46:47], v[14:15], v[22:23]
	s_nop 0
	v_pk_add_f32 v[22:23], v[50:51], v[22:23]
	s_nop 0
	v_mul_f32_e32 v102, 0xbfb8aa3b, v22
	v_mul_f32_e32 v103, 0xbfb8aa3b, v23
	v_exp_f32_e32 v102, v102
	v_exp_f32_e32 v103, v103
	v_add_f32_e32 v102, 1.0, v102
	v_add_f32_e32 v103, 1.0, v103
	v_rcp_f32_e32 v102, v102
	v_rcp_f32_e32 v103, v103
	s_nop 0
	v_pk_mul_f32 v[22:23], v[22:23], v[102:103]
	v_pk_mul_f32 v[102:103], v[44:45], v[8:9]
	v_pk_mul_f32 v[22:23], v[22:23], v[100:101]
	v_pk_fma_f32 v[24:25], v[28:29], v[24:25], v[102:103]
	v_cvt_pk_bf16_f32 v20, v22, v23
	v_pk_fma_f32 v[24:25], v[48:49], v[16:17], v[24:25]
	s_nop 0
	v_pk_add_f32 v[24:25], v[52:53], v[24:25]
	s_nop 0
	v_mul_f32_e32 v102, 0xbfb8aa3b, v24
	v_mul_f32_e32 v103, 0xbfb8aa3b, v25
	v_exp_f32_e32 v102, v102
	v_exp_f32_e32 v103, v103
	v_add_f32_e32 v102, 1.0, v102
	v_add_f32_e32 v103, 1.0, v103
	v_rcp_f32_e32 v102, v102
	v_rcp_f32_e32 v103, v103
	s_nop 0
	v_pk_mul_f32 v[24:25], v[24:25], v[102:103]
	s_nop 0
	v_pk_mul_f32 v[24:25], v[24:25], v[104:105]
	s_nop 0
	v_cvt_pk_bf16_f32 v21, v24, v25
	global_store_dwordx4 v[70:71], v[18:21], off
	v_add_co_u32_e32 v114, vcc, 0x9a00, v72
	s_nop 1
	v_addc_co_u32_e32 v115, vcc, 0, v73, vcc
	global_load_dwordx4 v[98:101], v[114:115], off
	v_add_co_u32_e32 v114, vcc, 0xb000, v72
	s_nop 1
	v_addc_co_u32_e32 v115, vcc, 0, v73, vcc
	global_load_dwordx4 v[102:105], v[114:115], off
	s_nop 1
	v_mov_b64_e32 v[18:19], 0
	s_and_saveexec_b64 s[12:13], s[16:17]
	s_cbranch_execz .Lffn2_485
	s_load_dwordx2 s[16:17], s[46:47], 0x128
	v_add_u32_e32 v18, 0xffffc002, v75
	v_mov_b32_e32 v19, v1
	v_lshl_add_u64 v[18:19], s[6:7], 0, v[18:19]
	s_movk_i32 s14, 0x2c00
	s_waitcnt lgkmcnt(0)
	v_mov_b64_e32 v[20:21], s[16:17]
	v_mad_u64_u32 v[20:21], s[16:17], v18, s14, v[20:21]
	v_mad_i32_i24 v21, v19, s14, v21
	v_lshl_add_u64 v[18:19], v[66:67], 2, v[20:21]
	s_mov_b64 s[16:17], 0x6aa7000
	v_lshl_add_u64 v[18:19], v[18:19], 0, s[16:17]

; DI void ffn_act(CP c, int l, int bid, int nb) {
;     ...
;     for (int r = r0; r < r1; ++r) {
;     ...
;         if (so) {
; #pragma unroll
;             for (int j = 0; j < 8; ++j) so[j] = a2[j]; }
;     }
.Lffn2_487:
	s_or_b64 exec, exec, s[12:13]
	v_cmp_ne_u64_e32 vcc, 0, v[18:19]
	s_and_saveexec_b64 s[12:13], vcc
	s_cbranch_execz .Lffn2_480
	global_store_dwordx4 v[18:19], v[10:13], off
	global_store_dwordx4 v[18:19], v[14:17], off offset:16
	s_branch .Lffn2_480
.Lffn2_480:
	s_or_b64 exec, exec, s[12:13]
	v_add_u32_e32 v75, 1, v75
	s_mov_b64 s[12:13], 0x1600
	v_lshl_add_u64 v[70:71], v[70:71], 0, s[12:13]
	v_cmp_ge_i32_e32 vcc, v75, v74
	s_mov_b64 s[12:13], 0x2c00
	s_or_b64 s[8:9], vcc, s[8:9]
	v_lshl_add_u64 v[72:73], v[72:73], 0, s[12:13]
	s_andn2_b64 exec, exec, s[8:9]
	s_cbranch_execz .LBB0_489

; DI void unpack8(u32x4 w, float* v) { v[0] = lo16(w.x); v[1] = hi16(w.x); v[2] = lo16(w.y); v[3] = hi16(w.y); v[4] = lo16(w.z); v[5] = hi16(w.z); v[6] = lo16(w.w); v[7] = hi16(w.w); }
; DI u32x4 pack8(const float* v) { u32x4 w; w.x = pk2(v[0], v[1]); w.y = pk2(v[2], v[3]); w.z = pk2(v[4], v[5]); w.w = pk2(v[6], v[7]); return w; }
; DI float silu(float x) { return x * __builtin_amdgcn_rcpf(1.f + fexp(-x)); }
; DI void ffn_act(CP c, int l, int bid, int nb) {
;     ...
;         const bool samp = r >= MP; const int b = (r - MP) >> 4, t = samp ? (r - MP) & 15 : r;
;         float a2[8], vv[8], o[8];
;         unpack8(*(const u32x4*)(UP + (size_t)r * 5632 + cc), a2); unpack8(*(const u32x4*)(UP + (size_t)r * 5632 + DFF + cc), vv);
;         if (r == r0 || (samp && t == 0)) {
;             if (t >= 1) unpack8(*(const u32x4*)(UP + (size_t)(r - 1) * 5632 + cc), a1);
;             else {
; #pragma unroll
;                 for (int j = 0; j < 8; ++j) a1[j] = samp ? c->in[I_SFFN][((size_t)(l * 32 + b) * 2 + 1) * DFF + cc + j] : 0.f; }
;             if (t >= 2) unpack8(*(const u32x4*)(UP + (size_t)(r - 2) * 5632 + cc), a0);
;             else {
; #pragma unroll
;                 for (int j = 0; j < 8; ++j) a0[j] = samp ? c->in[I_SFFN][((size_t)(l * 32 + b) * 2 + t) * DFF + cc + j] : 0.f; }
;         }
; #pragma unroll
;         for (int j = 0; j < 8; ++j) { const float y = w0[j] * a0[j] + w1[j] * a1[j] + w2[j] * a2[j] + bb[j]; o[j] = silu(y) * vv[j]; a0[j] = a1[j]; a1[j] = a2[j]; }
;         *(u32x4*)(ACT + (size_t)r * DFF + cc) = pack8(o);
.Lffn3_483:
	s_or_b64 exec, exec, s[12:13]
	v_pk_mul_f32 v[78:79], v[34:35], v[2:3]
	v_lshlrev_b32_e32 v10, 16, v106
	v_and_b32_e32 v11, 0xffff0000, v106
	v_pk_fma_f32 v[18:19], v[30:31], v[18:19], v[78:79]
	v_lshlrev_b32_e32 v12, 16, v107
	v_pk_fma_f32 v[18:19], v[38:39], v[10:11], v[18:19]
	v_and_b32_e32 v13, 0xffff0000, v107
	v_pk_add_f32 v[18:19], v[54:55], v[18:19]
	v_lshlrev_b32_e32 v106, 16, v110
	v_mul_f32_e32 v78, 0xbfb8aa3b, v18
	v_mul_f32_e32 v79, 0xbfb8aa3b, v19
	v_exp_f32_e32 v78, v78
	v_exp_f32_e32 v79, v79
	v_and_b32_e32 v107, 0xffff0000, v110
	v_lshlrev_b32_e32 v110, 16, v111
	v_add_f32_e32 v78, 1.0, v78
	v_add_f32_e32 v79, 1.0, v79
	v_rcp_f32_e32 v78, v78
	v_rcp_f32_e32 v79, v79
	v_and_b32_e32 v111, 0xffff0000, v111
	v_lshlrev_b32_e32 v14, 16, v108
	v_and_b32_e32 v15, 0xffff0000, v108
	v_pk_mul_f32 v[18:19], v[18:19], v[78:79]
	v_lshlrev_b32_e32 v16, 16, v109
	v_pk_mul_f32 v[18:19], v[18:19], v[106:107]
	v_pk_mul_f32 v[106:107], v[36:37], v[4:5]
	v_and_b32_e32 v17, 0xffff0000, v109
	v_pk_fma_f32 v[20:21], v[32:33], v[20:21], v[106:107]
	v_lshlrev_b32_e32 v108, 16, v112
	v_pk_fma_f32 v[20:21], v[40:41], v[12:13], v[20:21]
	v_and_b32_e32 v109, 0xffff0000, v112
	v_pk_add_f32 v[20:21], v[56:57], v[20:21]
	v_lshlrev_b32_e32 v112, 16, v113
	v_mul_f32_e32 v106, 0xbfb8aa3b, v20
	v_mul_f32_e32 v107, 0xbfb8aa3b, v21
	v_exp_f32_e32 v106, v106
	v_exp_f32_e32 v107, v107
	v_and_b32_e32 v113, 0xffff0000, v113
	s_movk_i32 s12, 0x3ffd
	v_add_f32_e32 v106, 1.0, v106
	v_add_f32_e32 v107, 1.0, v107
	v_rcp_f32_e32 v106, v106
	v_rcp_f32_e32 v107, v107
	v_cvt_pk_bf16_f32 v18, v18, v19
	v_cmp_lt_i32_e32 vcc, s12, v75
	s_xor_b64 s[16:17], s[38:39], vcc
	v_pk_mul_f32 v[20:21], v[20:21], v[106:107]
	s_nop 0
	v_pk_mul_f32 v[20:21], v[20:21], v[110:111]
	v_pk_mul_f32 v[110:111], v[42:43], v[6:7]
	v_cvt_pk_bf16_f32 v19, v20, v21
	v_pk_fma_f32 v[22:23], v[26:27], v[22:23], v[110:111]
	s_nop 0
	v_pk_fma_f32 v[22:23], v[46:47], v[14:15], v[22:23]
	s_nop 0
	v_pk_add_f32 v[22:23], v[50:51], v[22:23]
	s_nop 0
	v_mul_f32_e32 v110, 0xbfb8aa3b, v22
	v_mul_f32_e32 v111, 0xbfb8aa3b, v23
	v_exp_f32_e32 v110, v110
	v_exp_f32_e32 v111, v111
	v_add_f32_e32 v110, 1.0, v110
	v_add_f32_e32 v111, 1.0, v111
	v_rcp_f32_e32 v110, v110
	v_rcp_f32_e32 v111, v111
	s_nop 0
	v_pk_mul_f32 v[22:23], v[22:23], v[110:111]
	v_pk_mul_f32 v[110:111], v[44:45], v[8:9]
	v_pk_mul_f32 v[22:23], v[22:23], v[108:109]
	v_pk_fma_f32 v[24:25], v[28:29], v[24:25], v[110:111]
	v_cvt_pk_bf16_f32 v20, v22, v23
	v_pk_fma_f32 v[24:25], v[48:49], v[16:17], v[24:25]
	s_nop 0
	v_pk_add_f32 v[24:25], v[52:53], v[24:25]
	s_nop 0
	v_mul_f32_e32 v110, 0xbfb8aa3b, v24
	v_mul_f32_e32 v111, 0xbfb8aa3b, v25
	v_exp_f32_e32 v110, v110
	v_exp_f32_e32 v111, v111
	v_add_f32_e32 v110, 1.0, v110
	v_add_f32_e32 v111, 1.0, v111
	v_rcp_f32_e32 v110, v110
	v_rcp_f32_e32 v111, v111
	s_nop 0
	v_pk_mul_f32 v[24:25], v[24:25], v[110:111]
	s_nop 0
	v_pk_mul_f32 v[24:25], v[24:25], v[112:113]
	s_nop 0
	v_cvt_pk_bf16_f32 v21, v24, v25
	global_store_dwordx4 v[70:71], v[18:21], off
	v_add_co_u32_e32 v114, vcc, 0x9a00, v72
	s_nop 1
	v_addc_co_u32_e32 v115, vcc, 0, v73, vcc
	global_load_dwordx4 v[106:109], v[114:115], off
	v_add_co_u32_e32 v114, vcc, 0xb000, v72
	s_nop 1
	v_addc_co_u32_e32 v115, vcc, 0, v73, vcc
	global_load_dwordx4 v[110:113], v[114:115], off
	s_nop 1
	v_mov_b64_e32 v[18:19], 0
	s_and_saveexec_b64 s[12:13], s[16:17]
	s_cbranch_execz .Lffn3_485
	s_load_dwordx2 s[16:17], s[46:47], 0x128
	v_add_u32_e32 v18, 0xffffc002, v75
	v_mov_b32_e32 v19, v1
	v_lshl_add_u64 v[18:19], s[6:7], 0, v[18:19]
	s_movk_i32 s14, 0x2c00
	s_waitcnt lgkmcnt(0)
	v_mov_b64_e32 v[20:21], s[16:17]
	v_mad_u64_u32 v[20:21], s[16:17], v18, s14, v[20:21]
	v_mad_i32_i24 v21, v19, s14, v21
	v_lshl_add_u64 v[18:19], v[66:67], 2, v[20:21]
	s_mov_b64 s[16:17], 0x6aa7000
	v_lshl_add_u64 v[18:19], v[18:19], 0, s[16:17]

; DI void ffn_act(CP c, int l, int bid, int nb) {
;     ...
;     for (int r = r0; r < r1; ++r) {
.Lffn3_480:
	s_or_b64 exec, exec, s[12:13]
	v_add_u32_e32 v75, 1, v75
	s_mov_b64 s[12:13], 0x1600
	v_lshl_add_u64 v[70:71], v[70:71], 0, s[12:13]
	v_cmp_ge_i32_e32 vcc, v75, v74
	s_mov_b64 s[12:13], 0x2c00
	s_or_b64 s[8:9], vcc, s[8:9]
	v_lshl_add_u64 v[72:73], v[72:73], 0, s[12:13]
	s_andn2_b64 exec, exec, s[8:9]
	s_cbranch_execz .LBB0_489
	s_branch .Lffn0_481
